# attention tile loop software-pipelined: QK of next tile interleaved with exp of current, 256 VGPRs
# baseline (speedup 1.0000x reference)
.LBB0_1170:
	s_mul_i32 s27, s33, 0x8a00
	v_lshlrev_b32_e32 v197, 2, v174
	v_sub_u32_e32 v197, v149, v197
	v_readfirstlane_b32 s72, v180
	s_and_b32 s74, s25, -3
	s_cmp_eq_u32 s74, 0
	s_cbranch_scc0 .Lat_nomk
	s_cmp_eq_u32 s25, 0
	s_cbranch_scc0 .Lat_mk2
	v_cmp_ge_i32_e64 s[76:77], 0, v197
	v_cmp_ge_i32_e64 s[78:79], 1, v197
	v_cmp_ge_i32_e64 s[80:81], 2, v197
	v_cmp_ge_i32_e64 s[82:83], 3, v197
	v_cmp_ge_i32_e64 s[84:85], 8, v197
	v_cmp_ge_i32_e64 s[86:87], 9, v197
	v_cmp_ge_i32_e64 s[88:89], 10, v197
	v_cmp_ge_i32_e64 s[90:91], 11, v197
	v_cmp_ge_i32_e64 s[92:93], 16, v197
	v_cmp_ge_i32_e64 s[94:95], 17, v197
	v_cmp_ge_i32_e64 s[96:97], 18, v197
	v_cmp_ge_i32_e64 s[0:1], 19, v197
	v_cmp_ge_i32_e64 s[2:3], 24, v197
	v_cmp_ge_i32_e64 s[4:5], 25, v197
	v_cmp_ge_i32_e64 s[6:7], 26, v197
	v_cmp_ge_i32_e64 s[16:17], 27, v197
	s_branch .Lat_nomk
.Lat_mk2:
	v_cmp_le_i32_e64 s[76:77], 0, v197
	v_cmp_le_i32_e64 s[78:79], 1, v197
	v_cmp_le_i32_e64 s[80:81], 2, v197
	v_cmp_le_i32_e64 s[82:83], 3, v197
	v_cmp_le_i32_e64 s[84:85], 8, v197
	v_cmp_le_i32_e64 s[86:87], 9, v197
	v_cmp_le_i32_e64 s[88:89], 10, v197
	v_cmp_le_i32_e64 s[90:91], 11, v197
	v_cmp_le_i32_e64 s[92:93], 16, v197
	v_cmp_le_i32_e64 s[94:95], 17, v197
	v_cmp_le_i32_e64 s[96:97], 18, v197
	v_cmp_le_i32_e64 s[0:1], 19, v197
	v_cmp_le_i32_e64 s[2:3], 24, v197
	v_cmp_le_i32_e64 s[4:5], 25, v197
	v_cmp_le_i32_e64 s[6:7], 26, v197
	v_cmp_le_i32_e64 s[16:17], 27, v197
.Lat_nomk:
	s_nop 1
	s_cmp_eq_u32 s25, 0
	s_cselect_b32 s70, s72, 0
	s_cmp_eq_u32 s25, 2
	s_cselect_b32 s71, s72, 3
	s_and_b32 s74, s25, -3
	s_cmp_eq_u32 s74, 0
	s_cselect_b32 s73, s72, -1
	s_lshl_b32 s75, s70, 6
	s_add_i32 s75, s75, s27
	s_mul_i32 s19, s70, 0x1200
	s_add_i32 s19, s19, s27
	v_add_u32_e32 v199, s75, v184
	v_add_u32_e32 v198, s19, v185
	v_add_u32_e32 v200, 0x2000, v199
	ds_read_b128 v[220:223], v198
	ds_read_b128 v[224:227], v198 offset:32
	ds_read_b128 v[228:231], v198 offset:64
	ds_read_b128 v[232:235], v198 offset:96
	s_waitcnt lgkmcnt(3)
	v_mfma_f32_32x32x16_bf16 v[80:95], v[220:223], v[96:99], v[0:15]
	s_waitcnt lgkmcnt(2)
	v_mfma_f32_32x32x16_bf16 v[80:95], v[224:227], v[100:103], v[80:95]
	s_waitcnt lgkmcnt(1)
	v_mfma_f32_32x32x16_bf16 v[80:95], v[228:231], v[104:107], v[80:95]
	s_waitcnt lgkmcnt(0)
	v_mfma_f32_32x32x16_bf16 v[80:95], v[232:235], v[108:111], v[80:95]
	v_add_u32_e32 v198, 0x1200, v198
	ds_read_b128 v[220:223], v198
	ds_read_b128 v[224:227], v198 offset:32
	ds_read_b128 v[228:231], v198 offset:64
	ds_read_b128 v[232:235], v198 offset:96
	ds_read2_b64 v[236:239], v199 offset1:2
	ds_read2_b64 v[244:247], v200 offset0:32 offset1:34
	ds_read2_b64 v[248:251], v199 offset0:4 offset1:6
	ds_read2_b64 v[252:255], v200 offset0:36 offset1:38
	v_add_u32_e32 v199, 64, v199
	v_add_u32_e32 v200, 64, v200
	s_nop 1
	s_cmp_lt_u32 s70, s71
	s_cbranch_scc0 .Lat0_t0_last
	s_waitcnt lgkmcnt(7)
	v_mfma_f32_32x32x16_bf16 v[204:219], v[220:223], v[96:99], v[0:15]
	v_exp_f32_e32 v80, v80
	v_exp_f32_e32 v81, v81
	v_exp_f32_e32 v82, v82
	v_exp_f32_e32 v83, v83
	s_waitcnt lgkmcnt(6)
	v_mfma_f32_32x32x16_bf16 v[204:219], v[224:227], v[100:103], v[204:219]
	v_exp_f32_e32 v84, v84
	v_exp_f32_e32 v85, v85
	v_exp_f32_e32 v86, v86
	v_exp_f32_e32 v87, v87
	s_waitcnt lgkmcnt(5)
	v_mfma_f32_32x32x16_bf16 v[204:219], v[228:231], v[104:107], v[204:219]
	v_exp_f32_e32 v88, v88
	v_exp_f32_e32 v89, v89
	v_exp_f32_e32 v90, v90
	v_exp_f32_e32 v91, v91
	s_waitcnt lgkmcnt(4)
	v_mfma_f32_32x32x16_bf16 v[204:219], v[232:235], v[108:111], v[204:219]
	v_exp_f32_e32 v92, v92
	v_exp_f32_e32 v93, v93
	v_exp_f32_e32 v94, v94
	v_exp_f32_e32 v95, v95
	s_branch .Lat0_t0_soft
.Lat0_t0_last:
	v_exp_f32_e32 v80, v80
	v_exp_f32_e32 v81, v81
	v_exp_f32_e32 v82, v82
	v_exp_f32_e32 v83, v83
	v_exp_f32_e32 v84, v84
	v_exp_f32_e32 v85, v85
	v_exp_f32_e32 v86, v86
	v_exp_f32_e32 v87, v87
	v_exp_f32_e32 v88, v88
	v_exp_f32_e32 v89, v89
	v_exp_f32_e32 v90, v90
	v_exp_f32_e32 v91, v91
	v_exp_f32_e32 v92, v92
	v_exp_f32_e32 v93, v93
	v_exp_f32_e32 v94, v94
	v_exp_f32_e32 v95, v95
.Lat0_t0_soft:
	v_add_u32_e32 v198, 0x1200, v198
	ds_read_b128 v[220:223], v198
	ds_read_b128 v[224:227], v198 offset:32
	ds_read_b128 v[228:231], v198 offset:64
	ds_read_b128 v[232:235], v198 offset:96
	s_cmp_eq_u32 s70, s73
	s_cbranch_scc0 .Lat0_t0_nomask
	v_cndmask_b32_e64 v80, 0, v80, s[76:77]
	v_cndmask_b32_e64 v81, 0, v81, s[78:79]
	v_cndmask_b32_e64 v82, 0, v82, s[80:81]
	v_cndmask_b32_e64 v83, 0, v83, s[82:83]
	v_cndmask_b32_e64 v84, 0, v84, s[84:85]
	v_cndmask_b32_e64 v85, 0, v85, s[86:87]
	v_cndmask_b32_e64 v86, 0, v86, s[88:89]
	v_cndmask_b32_e64 v87, 0, v87, s[90:91]
	v_cndmask_b32_e64 v88, 0, v88, s[92:93]
	v_cndmask_b32_e64 v89, 0, v89, s[94:95]
	v_cndmask_b32_e64 v90, 0, v90, s[96:97]
	v_cndmask_b32_e64 v91, 0, v91, s[0:1]
	v_cndmask_b32_e64 v92, 0, v92, s[2:3]
	v_cndmask_b32_e64 v93, 0, v93, s[4:5]
	v_cndmask_b32_e64 v94, 0, v94, s[6:7]
	v_cndmask_b32_e64 v95, 0, v95, s[16:17]
.Lat0_t0_nomask:
	v_add_f32_e32 v189, v80, v81
	v_add_f32_e32 v190, v82, v83
	v_add_f32_e32 v191, v84, v85
	v_add_f32_e32 v192, v86, v87
	v_cvt_pk_bf16_f32 v80, v80, v81
	v_cvt_pk_bf16_f32 v81, v82, v83
	v_cvt_pk_bf16_f32 v82, v84, v85
	v_cvt_pk_bf16_f32 v83, v86, v87
	v_add_f32_e32 v193, v88, v89
	v_add_f32_e32 v194, v90, v91
	s_waitcnt lgkmcnt(4)
	v_mfma_f32_32x32x16_bf16 v[64:79], v[236:239], v[80:83], v[64:79]
	v_add_f32_e32 v195, v92, v93
	v_add_f32_e32 v196, v94, v95
	v_cvt_pk_bf16_f32 v84, v88, v89
	v_cvt_pk_bf16_f32 v85, v90, v91
	v_mfma_f32_32x32x16_bf16 v[48:63], v[244:247], v[80:83], v[48:63]
	v_cvt_pk_bf16_f32 v86, v92, v93
	v_cvt_pk_bf16_f32 v87, v94, v95
	v_add_f32_e32 v189, v189, v190
	v_add_f32_e32 v191, v191, v192
	v_mfma_f32_32x32x16_bf16 v[64:79], v[248:251], v[84:87], v[64:79]
	v_add_f32_e32 v193, v193, v194
	v_add_f32_e32 v195, v195, v196
	v_add_f32_e32 v189, v189, v191
	v_add_f32_e32 v193, v193, v195
	v_mfma_f32_32x32x16_bf16 v[48:63], v[252:255], v[84:87], v[48:63]
	v_add_f32_e32 v189, v189, v193
	v_add_f32_e32 v188, v188, v189
	ds_read2_b64 v[236:239], v199 offset1:2
	ds_read2_b64 v[244:247], v200 offset0:32 offset1:34
	ds_read2_b64 v[248:251], v199 offset0:4 offset1:6
	ds_read2_b64 v[252:255], v200 offset0:36 offset1:38
	v_add_u32_e32 v199, 64, v199
	v_add_u32_e32 v200, 64, v200
	s_add_i32 s70, s70, 1
	s_cmp_le_u32 s70, s71
	s_cbranch_scc0 .Lat0_done
	s_cmp_lt_u32 s70, s71
	s_cbranch_scc0 .Lat0_t1_last
	s_waitcnt lgkmcnt(7)
	v_mfma_f32_32x32x16_bf16 v[80:95], v[220:223], v[96:99], v[0:15]
	v_exp_f32_e32 v204, v204
	v_exp_f32_e32 v205, v205
	v_exp_f32_e32 v206, v206
	v_exp_f32_e32 v207, v207
	s_waitcnt lgkmcnt(6)
	v_mfma_f32_32x32x16_bf16 v[80:95], v[224:227], v[100:103], v[80:95]
	v_exp_f32_e32 v208, v208
	v_exp_f32_e32 v209, v209
	v_exp_f32_e32 v210, v210
	v_exp_f32_e32 v211, v211
	s_waitcnt lgkmcnt(5)
	v_mfma_f32_32x32x16_bf16 v[80:95], v[228:231], v[104:107], v[80:95]
	v_exp_f32_e32 v212, v212
	v_exp_f32_e32 v213, v213
	v_exp_f32_e32 v214, v214
	v_exp_f32_e32 v215, v215
	s_waitcnt lgkmcnt(4)
	v_mfma_f32_32x32x16_bf16 v[80:95], v[232:235], v[108:111], v[80:95]
	v_exp_f32_e32 v216, v216
	v_exp_f32_e32 v217, v217
	v_exp_f32_e32 v218, v218
	v_exp_f32_e32 v219, v219
	s_branch .Lat0_t1_soft
.Lat0_t1_last:
	v_exp_f32_e32 v204, v204
	v_exp_f32_e32 v205, v205
	v_exp_f32_e32 v206, v206
	v_exp_f32_e32 v207, v207
	v_exp_f32_e32 v208, v208
	v_exp_f32_e32 v209, v209
	v_exp_f32_e32 v210, v210
	v_exp_f32_e32 v211, v211
	v_exp_f32_e32 v212, v212
	v_exp_f32_e32 v213, v213
	v_exp_f32_e32 v214, v214
	v_exp_f32_e32 v215, v215
	v_exp_f32_e32 v216, v216
	v_exp_f32_e32 v217, v217
	v_exp_f32_e32 v218, v218
	v_exp_f32_e32 v219, v219
.Lat0_t1_soft:
	v_add_u32_e32 v198, 0x1200, v198
	ds_read_b128 v[220:223], v198
	ds_read_b128 v[224:227], v198 offset:32
	ds_read_b128 v[228:231], v198 offset:64
	ds_read_b128 v[232:235], v198 offset:96
	s_cmp_eq_u32 s70, s73
	s_cbranch_scc0 .Lat0_t1_nomask
	v_cndmask_b32_e64 v204, 0, v204, s[76:77]
	v_cndmask_b32_e64 v205, 0, v205, s[78:79]
	v_cndmask_b32_e64 v206, 0, v206, s[80:81]
	v_cndmask_b32_e64 v207, 0, v207, s[82:83]
	v_cndmask_b32_e64 v208, 0, v208, s[84:85]
	v_cndmask_b32_e64 v209, 0, v209, s[86:87]
	v_cndmask_b32_e64 v210, 0, v210, s[88:89]
	v_cndmask_b32_e64 v211, 0, v211, s[90:91]
	v_cndmask_b32_e64 v212, 0, v212, s[92:93]
	v_cndmask_b32_e64 v213, 0, v213, s[94:95]
	v_cndmask_b32_e64 v214, 0, v214, s[96:97]
	v_cndmask_b32_e64 v215, 0, v215, s[0:1]
	v_cndmask_b32_e64 v216, 0, v216, s[2:3]
	v_cndmask_b32_e64 v217, 0, v217, s[4:5]
	v_cndmask_b32_e64 v218, 0, v218, s[6:7]
	v_cndmask_b32_e64 v219, 0, v219, s[16:17]
.Lat0_t1_nomask:
	v_add_f32_e32 v189, v204, v205
	v_add_f32_e32 v190, v206, v207
	v_add_f32_e32 v191, v208, v209
	v_add_f32_e32 v192, v210, v211
	v_cvt_pk_bf16_f32 v204, v204, v205
	v_cvt_pk_bf16_f32 v205, v206, v207
	v_cvt_pk_bf16_f32 v206, v208, v209
	v_cvt_pk_bf16_f32 v207, v210, v211
	v_add_f32_e32 v193, v212, v213
	v_add_f32_e32 v194, v214, v215
	s_waitcnt lgkmcnt(4)
	v_mfma_f32_32x32x16_bf16 v[64:79], v[236:239], v[204:207], v[64:79]
	v_add_f32_e32 v195, v216, v217
	v_add_f32_e32 v196, v218, v219
	v_cvt_pk_bf16_f32 v208, v212, v213
	v_cvt_pk_bf16_f32 v209, v214, v215
	v_mfma_f32_32x32x16_bf16 v[48:63], v[244:247], v[204:207], v[48:63]
	v_cvt_pk_bf16_f32 v210, v216, v217
	v_cvt_pk_bf16_f32 v211, v218, v219
	v_add_f32_e32 v189, v189, v190
	v_add_f32_e32 v191, v191, v192
	v_mfma_f32_32x32x16_bf16 v[64:79], v[248:251], v[208:211], v[64:79]
	v_add_f32_e32 v193, v193, v194
	v_add_f32_e32 v195, v195, v196
	v_add_f32_e32 v189, v189, v191
	v_add_f32_e32 v193, v193, v195
	v_mfma_f32_32x32x16_bf16 v[48:63], v[252:255], v[208:211], v[48:63]
	v_add_f32_e32 v189, v189, v193
	v_add_f32_e32 v188, v188, v189
	ds_read2_b64 v[236:239], v199 offset1:2
	ds_read2_b64 v[244:247], v200 offset0:32 offset1:34
	ds_read2_b64 v[248:251], v199 offset0:4 offset1:6
	ds_read2_b64 v[252:255], v200 offset0:36 offset1:38
	v_add_u32_e32 v199, 64, v199
	v_add_u32_e32 v200, 64, v200
	s_add_i32 s70, s70, 1
	s_cmp_le_u32 s70, s71
	s_cbranch_scc0 .Lat0_done
	s_cmp_lt_u32 s70, s71
	s_cbranch_scc0 .Lat0_t2_last
	s_waitcnt lgkmcnt(7)
	v_mfma_f32_32x32x16_bf16 v[204:219], v[220:223], v[96:99], v[0:15]
	v_exp_f32_e32 v80, v80
	v_exp_f32_e32 v81, v81
	v_exp_f32_e32 v82, v82
	v_exp_f32_e32 v83, v83
	s_waitcnt lgkmcnt(6)
	v_mfma_f32_32x32x16_bf16 v[204:219], v[224:227], v[100:103], v[204:219]
	v_exp_f32_e32 v84, v84
	v_exp_f32_e32 v85, v85
	v_exp_f32_e32 v86, v86
	v_exp_f32_e32 v87, v87
	s_waitcnt lgkmcnt(5)
	v_mfma_f32_32x32x16_bf16 v[204:219], v[228:231], v[104:107], v[204:219]
	v_exp_f32_e32 v88, v88
	v_exp_f32_e32 v89, v89
	v_exp_f32_e32 v90, v90
	v_exp_f32_e32 v91, v91
	s_waitcnt lgkmcnt(4)
	v_mfma_f32_32x32x16_bf16 v[204:219], v[232:235], v[108:111], v[204:219]
	v_exp_f32_e32 v92, v92
	v_exp_f32_e32 v93, v93
	v_exp_f32_e32 v94, v94
	v_exp_f32_e32 v95, v95
	s_branch .Lat0_t2_soft

.Lat0_t2_nomask:
	v_add_f32_e32 v189, v80, v81
	v_add_f32_e32 v190, v82, v83
	v_add_f32_e32 v191, v84, v85
	v_add_f32_e32 v192, v86, v87
	v_cvt_pk_bf16_f32 v80, v80, v81
	v_cvt_pk_bf16_f32 v81, v82, v83
	v_cvt_pk_bf16_f32 v82, v84, v85
	v_cvt_pk_bf16_f32 v83, v86, v87
	v_add_f32_e32 v193, v88, v89
	v_add_f32_e32 v194, v90, v91
	s_waitcnt lgkmcnt(4)
	v_mfma_f32_32x32x16_bf16 v[64:79], v[236:239], v[80:83], v[64:79]
	v_add_f32_e32 v195, v92, v93
	v_add_f32_e32 v196, v94, v95
	v_cvt_pk_bf16_f32 v84, v88, v89
	v_cvt_pk_bf16_f32 v85, v90, v91
	v_mfma_f32_32x32x16_bf16 v[48:63], v[244:247], v[80:83], v[48:63]
	v_cvt_pk_bf16_f32 v86, v92, v93
	v_cvt_pk_bf16_f32 v87, v94, v95
	v_add_f32_e32 v189, v189, v190
	v_add_f32_e32 v191, v191, v192
	v_mfma_f32_32x32x16_bf16 v[64:79], v[248:251], v[84:87], v[64:79]
	v_add_f32_e32 v193, v193, v194
	v_add_f32_e32 v195, v195, v196
	v_add_f32_e32 v189, v189, v191
	v_add_f32_e32 v193, v193, v195
	v_mfma_f32_32x32x16_bf16 v[48:63], v[252:255], v[84:87], v[48:63]
	v_add_f32_e32 v189, v189, v193
	v_add_f32_e32 v188, v188, v189
	ds_read2_b64 v[236:239], v199 offset1:2
	ds_read2_b64 v[244:247], v200 offset0:32 offset1:34
	ds_read2_b64 v[248:251], v199 offset0:4 offset1:6
	ds_read2_b64 v[252:255], v200 offset0:36 offset1:38
	v_add_u32_e32 v199, 64, v199
	v_add_u32_e32 v200, 64, v200
	s_add_i32 s70, s70, 1
	s_cmp_le_u32 s70, s71
	s_cbranch_scc0 .Lat0_done
	v_exp_f32_e32 v204, v204
	v_exp_f32_e32 v205, v205
	v_exp_f32_e32 v206, v206
	v_exp_f32_e32 v207, v207
	v_exp_f32_e32 v208, v208
	v_exp_f32_e32 v209, v209
	v_exp_f32_e32 v210, v210
	v_exp_f32_e32 v211, v211
	v_exp_f32_e32 v212, v212
	v_exp_f32_e32 v213, v213
	v_exp_f32_e32 v214, v214
	v_exp_f32_e32 v215, v215
	v_exp_f32_e32 v216, v216
	v_exp_f32_e32 v217, v217
	v_exp_f32_e32 v218, v218
	v_exp_f32_e32 v219, v219
	v_add_u32_e32 v198, 0x1200, v198
	ds_read_b128 v[220:223], v198
	ds_read_b128 v[224:227], v198 offset:32
	ds_read_b128 v[228:231], v198 offset:64
	ds_read_b128 v[232:235], v198 offset:96
	s_cmp_eq_u32 s70, s73
	s_cbranch_scc0 .Lat0_t3_nomask
	v_cndmask_b32_e64 v204, 0, v204, s[76:77]
	v_cndmask_b32_e64 v205, 0, v205, s[78:79]
	v_cndmask_b32_e64 v206, 0, v206, s[80:81]
	v_cndmask_b32_e64 v207, 0, v207, s[82:83]
	v_cndmask_b32_e64 v208, 0, v208, s[84:85]
	v_cndmask_b32_e64 v209, 0, v209, s[86:87]
	v_cndmask_b32_e64 v210, 0, v210, s[88:89]
	v_cndmask_b32_e64 v211, 0, v211, s[90:91]
	v_cndmask_b32_e64 v212, 0, v212, s[92:93]
	v_cndmask_b32_e64 v213, 0, v213, s[94:95]
	v_cndmask_b32_e64 v214, 0, v214, s[96:97]
	v_cndmask_b32_e64 v215, 0, v215, s[0:1]
	v_cndmask_b32_e64 v216, 0, v216, s[2:3]
	v_cndmask_b32_e64 v217, 0, v217, s[4:5]
	v_cndmask_b32_e64 v218, 0, v218, s[6:7]
	v_cndmask_b32_e64 v219, 0, v219, s[16:17]
.Lat0_t3_nomask:
	v_add_f32_e32 v189, v204, v205
	v_add_f32_e32 v190, v206, v207
	v_add_f32_e32 v191, v208, v209
	v_add_f32_e32 v192, v210, v211
	v_cvt_pk_bf16_f32 v204, v204, v205
	v_cvt_pk_bf16_f32 v205, v206, v207
	v_cvt_pk_bf16_f32 v206, v208, v209
	v_cvt_pk_bf16_f32 v207, v210, v211
	v_add_f32_e32 v193, v212, v213
	v_add_f32_e32 v194, v214, v215
	s_waitcnt lgkmcnt(4)
	v_mfma_f32_32x32x16_bf16 v[64:79], v[236:239], v[204:207], v[64:79]
	v_add_f32_e32 v195, v216, v217
	v_add_f32_e32 v196, v218, v219
	v_cvt_pk_bf16_f32 v208, v212, v213
	v_cvt_pk_bf16_f32 v209, v214, v215
	v_mfma_f32_32x32x16_bf16 v[48:63], v[244:247], v[204:207], v[48:63]
	v_cvt_pk_bf16_f32 v210, v216, v217
	v_cvt_pk_bf16_f32 v211, v218, v219
	v_add_f32_e32 v189, v189, v190
	v_add_f32_e32 v191, v191, v192
	v_mfma_f32_32x32x16_bf16 v[64:79], v[248:251], v[208:211], v[64:79]
	v_add_f32_e32 v193, v193, v194
	v_add_f32_e32 v195, v195, v196
	v_add_f32_e32 v189, v189, v191
	v_add_f32_e32 v193, v193, v195
	v_mfma_f32_32x32x16_bf16 v[48:63], v[252:255], v[208:211], v[48:63]
	v_add_f32_e32 v189, v189, v193
	v_add_f32_e32 v188, v188, v189
	ds_read2_b64 v[236:239], v199 offset1:2
	ds_read2_b64 v[244:247], v200 offset0:32 offset1:34
	ds_read2_b64 v[248:251], v199 offset0:4 offset1:6
	ds_read2_b64 v[252:255], v200 offset0:36 offset1:38
	v_add_u32_e32 v199, 64, v199
	v_add_u32_e32 v200, 64, v200
.Lat0_done:
	s_or_b32 s72, s72, 1
	s_cmp_eq_u32 s25, 0
	s_cselect_b32 s70, s72, 0
	s_cmp_eq_u32 s25, 2
	s_cselect_b32 s71, s72, 3
	s_and_b32 s74, s25, -3
	s_cmp_eq_u32 s74, 0
	s_cselect_b32 s73, s72, -1
	s_lshl_b32 s75, s70, 6
	s_add_i32 s75, s75, s27
	s_mul_i32 s19, s70, 0x1200
	s_add_i32 s19, s19, s27
	v_add_u32_e32 v199, s75, v184
	v_add_u32_e32 v198, s19, v185
	v_add_u32_e32 v200, 0x2000, v199
	ds_read_b128 v[220:223], v198
	ds_read_b128 v[224:227], v198 offset:32
	ds_read_b128 v[228:231], v198 offset:64
	ds_read_b128 v[232:235], v198 offset:96
	s_waitcnt lgkmcnt(3)
	v_mfma_f32_32x32x16_bf16 v[80:95], v[220:223], v[128:131], v[0:15]
	s_waitcnt lgkmcnt(2)
	v_mfma_f32_32x32x16_bf16 v[80:95], v[224:227], v[132:135], v[80:95]
	s_waitcnt lgkmcnt(1)
	v_mfma_f32_32x32x16_bf16 v[80:95], v[228:231], v[136:139], v[80:95]
	s_waitcnt lgkmcnt(0)
	v_mfma_f32_32x32x16_bf16 v[80:95], v[232:235], v[140:143], v[80:95]
	v_add_u32_e32 v198, 0x1200, v198
	ds_read_b128 v[220:223], v198
	ds_read_b128 v[224:227], v198 offset:32
	ds_read_b128 v[228:231], v198 offset:64
	ds_read_b128 v[232:235], v198 offset:96
	ds_read2_b64 v[236:239], v199 offset1:2
	ds_read2_b64 v[244:247], v200 offset0:32 offset1:34
	ds_read2_b64 v[248:251], v199 offset0:4 offset1:6
	ds_read2_b64 v[252:255], v200 offset0:36 offset1:38
	v_add_u32_e32 v199, 64, v199
	v_add_u32_e32 v200, 64, v200
	s_nop 1
	s_cmp_lt_u32 s70, s71
	s_cbranch_scc0 .Lat1_t0_last
	s_waitcnt lgkmcnt(7)
	v_mfma_f32_32x32x16_bf16 v[204:219], v[220:223], v[128:131], v[0:15]
	v_exp_f32_e32 v80, v80
	v_exp_f32_e32 v81, v81
	v_exp_f32_e32 v82, v82
	v_exp_f32_e32 v83, v83
	s_waitcnt lgkmcnt(6)
	v_mfma_f32_32x32x16_bf16 v[204:219], v[224:227], v[132:135], v[204:219]
	v_exp_f32_e32 v84, v84
	v_exp_f32_e32 v85, v85
	v_exp_f32_e32 v86, v86
	v_exp_f32_e32 v87, v87
	s_waitcnt lgkmcnt(5)
	v_mfma_f32_32x32x16_bf16 v[204:219], v[228:231], v[136:139], v[204:219]
	v_exp_f32_e32 v88, v88
	v_exp_f32_e32 v89, v89
	v_exp_f32_e32 v90, v90
	v_exp_f32_e32 v91, v91
	s_waitcnt lgkmcnt(4)
	v_mfma_f32_32x32x16_bf16 v[204:219], v[232:235], v[140:143], v[204:219]
	v_exp_f32_e32 v92, v92
	v_exp_f32_e32 v93, v93
	v_exp_f32_e32 v94, v94
	v_exp_f32_e32 v95, v95
	s_branch .Lat1_t0_soft

.Lat1_t0_nomask:
	v_add_f32_e32 v189, v80, v81
	v_add_f32_e32 v190, v82, v83
	v_add_f32_e32 v191, v84, v85
	v_add_f32_e32 v192, v86, v87
	v_cvt_pk_bf16_f32 v80, v80, v81
	v_cvt_pk_bf16_f32 v81, v82, v83
	v_cvt_pk_bf16_f32 v82, v84, v85
	v_cvt_pk_bf16_f32 v83, v86, v87
	v_add_f32_e32 v193, v88, v89
	v_add_f32_e32 v194, v90, v91
	s_waitcnt lgkmcnt(4)
	v_mfma_f32_32x32x16_bf16 v[32:47], v[236:239], v[80:83], v[32:47]
	v_add_f32_e32 v195, v92, v93
	v_add_f32_e32 v196, v94, v95
	v_cvt_pk_bf16_f32 v84, v88, v89
	v_cvt_pk_bf16_f32 v85, v90, v91
	v_mfma_f32_32x32x16_bf16 v[16:31], v[244:247], v[80:83], v[16:31]
	v_cvt_pk_bf16_f32 v86, v92, v93
	v_cvt_pk_bf16_f32 v87, v94, v95
	v_add_f32_e32 v189, v189, v190
	v_add_f32_e32 v191, v191, v192
	v_mfma_f32_32x32x16_bf16 v[32:47], v[248:251], v[84:87], v[32:47]
	v_add_f32_e32 v193, v193, v194
	v_add_f32_e32 v195, v195, v196
	v_add_f32_e32 v189, v189, v191
	v_add_f32_e32 v193, v193, v195
	v_mfma_f32_32x32x16_bf16 v[16:31], v[252:255], v[84:87], v[16:31]
	v_add_f32_e32 v189, v189, v193
	v_add_f32_e32 v187, v187, v189
	ds_read2_b64 v[236:239], v199 offset1:2
	ds_read2_b64 v[244:247], v200 offset0:32 offset1:34
	ds_read2_b64 v[248:251], v199 offset0:4 offset1:6
	ds_read2_b64 v[252:255], v200 offset0:36 offset1:38
	v_add_u32_e32 v199, 64, v199
	v_add_u32_e32 v200, 64, v200
	s_add_i32 s70, s70, 1
	s_cmp_le_u32 s70, s71
	s_cbranch_scc0 .Lat1_done
	s_cmp_lt_u32 s70, s71
	s_cbranch_scc0 .Lat1_t1_last
	s_waitcnt lgkmcnt(7)
	v_mfma_f32_32x32x16_bf16 v[80:95], v[220:223], v[128:131], v[0:15]
	v_exp_f32_e32 v204, v204
	v_exp_f32_e32 v205, v205
	v_exp_f32_e32 v206, v206
	v_exp_f32_e32 v207, v207
	s_waitcnt lgkmcnt(6)
	v_mfma_f32_32x32x16_bf16 v[80:95], v[224:227], v[132:135], v[80:95]
	v_exp_f32_e32 v208, v208
	v_exp_f32_e32 v209, v209
	v_exp_f32_e32 v210, v210
	v_exp_f32_e32 v211, v211
	s_waitcnt lgkmcnt(5)
	v_mfma_f32_32x32x16_bf16 v[80:95], v[228:231], v[136:139], v[80:95]
	v_exp_f32_e32 v212, v212
	v_exp_f32_e32 v213, v213
	v_exp_f32_e32 v214, v214
	v_exp_f32_e32 v215, v215
	s_waitcnt lgkmcnt(4)
	v_mfma_f32_32x32x16_bf16 v[80:95], v[232:235], v[140:143], v[80:95]
	v_exp_f32_e32 v216, v216
	v_exp_f32_e32 v217, v217
	v_exp_f32_e32 v218, v218
	v_exp_f32_e32 v219, v219
	s_branch .Lat1_t1_soft

.Lat1_t1_nomask:
	v_add_f32_e32 v189, v204, v205
	v_add_f32_e32 v190, v206, v207
	v_add_f32_e32 v191, v208, v209
	v_add_f32_e32 v192, v210, v211
	v_cvt_pk_bf16_f32 v204, v204, v205
	v_cvt_pk_bf16_f32 v205, v206, v207
	v_cvt_pk_bf16_f32 v206, v208, v209
	v_cvt_pk_bf16_f32 v207, v210, v211
	v_add_f32_e32 v193, v212, v213
	v_add_f32_e32 v194, v214, v215
	s_waitcnt lgkmcnt(4)
	v_mfma_f32_32x32x16_bf16 v[32:47], v[236:239], v[204:207], v[32:47]
	v_add_f32_e32 v195, v216, v217
	v_add_f32_e32 v196, v218, v219
	v_cvt_pk_bf16_f32 v208, v212, v213
	v_cvt_pk_bf16_f32 v209, v214, v215
	v_mfma_f32_32x32x16_bf16 v[16:31], v[244:247], v[204:207], v[16:31]
	v_cvt_pk_bf16_f32 v210, v216, v217
	v_cvt_pk_bf16_f32 v211, v218, v219
	v_add_f32_e32 v189, v189, v190
	v_add_f32_e32 v191, v191, v192
	v_mfma_f32_32x32x16_bf16 v[32:47], v[248:251], v[208:211], v[32:47]
	v_add_f32_e32 v193, v193, v194
	v_add_f32_e32 v195, v195, v196
	v_add_f32_e32 v189, v189, v191
	v_add_f32_e32 v193, v193, v195
	v_mfma_f32_32x32x16_bf16 v[16:31], v[252:255], v[208:211], v[16:31]
	v_add_f32_e32 v189, v189, v193
	v_add_f32_e32 v187, v187, v189
	ds_read2_b64 v[236:239], v199 offset1:2
	ds_read2_b64 v[244:247], v200 offset0:32 offset1:34
	ds_read2_b64 v[248:251], v199 offset0:4 offset1:6
	ds_read2_b64 v[252:255], v200 offset0:36 offset1:38
	v_add_u32_e32 v199, 64, v199
	v_add_u32_e32 v200, 64, v200
	s_add_i32 s70, s70, 1
	s_cmp_le_u32 s70, s71
	s_cbranch_scc0 .Lat1_done
	s_cmp_lt_u32 s70, s71
	s_cbranch_scc0 .Lat1_t2_last
	s_waitcnt lgkmcnt(7)
	v_mfma_f32_32x32x16_bf16 v[204:219], v[220:223], v[128:131], v[0:15]
	v_exp_f32_e32 v80, v80
	v_exp_f32_e32 v81, v81
	v_exp_f32_e32 v82, v82
	v_exp_f32_e32 v83, v83
	s_waitcnt lgkmcnt(6)
	v_mfma_f32_32x32x16_bf16 v[204:219], v[224:227], v[132:135], v[204:219]
	v_exp_f32_e32 v84, v84
	v_exp_f32_e32 v85, v85
	v_exp_f32_e32 v86, v86
	v_exp_f32_e32 v87, v87
	s_waitcnt lgkmcnt(5)
	v_mfma_f32_32x32x16_bf16 v[204:219], v[228:231], v[136:139], v[204:219]
	v_exp_f32_e32 v88, v88
	v_exp_f32_e32 v89, v89
	v_exp_f32_e32 v90, v90
	v_exp_f32_e32 v91, v91
	s_waitcnt lgkmcnt(4)
	v_mfma_f32_32x32x16_bf16 v[204:219], v[232:235], v[140:143], v[204:219]
	v_exp_f32_e32 v92, v92
	v_exp_f32_e32 v93, v93
	v_exp_f32_e32 v94, v94
	v_exp_f32_e32 v95, v95
	s_branch .Lat1_t2_soft

.Lat1_t2_nomask:
	v_add_f32_e32 v189, v80, v81
	v_add_f32_e32 v190, v82, v83
	v_add_f32_e32 v191, v84, v85
	v_add_f32_e32 v192, v86, v87
	v_cvt_pk_bf16_f32 v80, v80, v81
	v_cvt_pk_bf16_f32 v81, v82, v83
	v_cvt_pk_bf16_f32 v82, v84, v85
	v_cvt_pk_bf16_f32 v83, v86, v87
	v_add_f32_e32 v193, v88, v89
	v_add_f32_e32 v194, v90, v91
	s_waitcnt lgkmcnt(4)
	v_mfma_f32_32x32x16_bf16 v[32:47], v[236:239], v[80:83], v[32:47]
	v_add_f32_e32 v195, v92, v93
	v_add_f32_e32 v196, v94, v95
	v_cvt_pk_bf16_f32 v84, v88, v89
	v_cvt_pk_bf16_f32 v85, v90, v91
	v_mfma_f32_32x32x16_bf16 v[16:31], v[244:247], v[80:83], v[16:31]
	v_cvt_pk_bf16_f32 v86, v92, v93
	v_cvt_pk_bf16_f32 v87, v94, v95
	v_add_f32_e32 v189, v189, v190
	v_add_f32_e32 v191, v191, v192
	v_mfma_f32_32x32x16_bf16 v[32:47], v[248:251], v[84:87], v[32:47]
	v_add_f32_e32 v193, v193, v194
	v_add_f32_e32 v195, v195, v196
	v_add_f32_e32 v189, v189, v191
	v_add_f32_e32 v193, v193, v195
	v_mfma_f32_32x32x16_bf16 v[16:31], v[252:255], v[84:87], v[16:31]
	v_add_f32_e32 v189, v189, v193
	v_add_f32_e32 v187, v187, v189
	ds_read2_b64 v[236:239], v199 offset1:2
	ds_read2_b64 v[244:247], v200 offset0:32 offset1:34
	ds_read2_b64 v[248:251], v199 offset0:4 offset1:6
	ds_read2_b64 v[252:255], v200 offset0:36 offset1:38
	v_add_u32_e32 v199, 64, v199
	v_add_u32_e32 v200, 64, v200
	s_add_i32 s70, s70, 1
	s_cmp_le_u32 s70, s71
	s_cbranch_scc0 .Lat1_done
	v_exp_f32_e32 v204, v204
	v_exp_f32_e32 v205, v205
	v_exp_f32_e32 v206, v206
	v_exp_f32_e32 v207, v207
	v_exp_f32_e32 v208, v208
	v_exp_f32_e32 v209, v209
	v_exp_f32_e32 v210, v210
	v_exp_f32_e32 v211, v211
	v_exp_f32_e32 v212, v212
	v_exp_f32_e32 v213, v213
	v_exp_f32_e32 v214, v214
	v_exp_f32_e32 v215, v215
	v_exp_f32_e32 v216, v216
	v_exp_f32_e32 v217, v217
	v_exp_f32_e32 v218, v218
	v_exp_f32_e32 v219, v219
	v_add_u32_e32 v198, 0x1200, v198
	ds_read_b128 v[220:223], v198
	ds_read_b128 v[224:227], v198 offset:32
	ds_read_b128 v[228:231], v198 offset:64
	ds_read_b128 v[232:235], v198 offset:96
	s_cmp_eq_u32 s70, s73
	s_cbranch_scc0 .Lat1_t3_nomask
	v_cndmask_b32_e64 v204, 0, v204, s[76:77]
	v_cndmask_b32_e64 v205, 0, v205, s[78:79]
	v_cndmask_b32_e64 v206, 0, v206, s[80:81]
	v_cndmask_b32_e64 v207, 0, v207, s[82:83]
	v_cndmask_b32_e64 v208, 0, v208, s[84:85]
	v_cndmask_b32_e64 v209, 0, v209, s[86:87]
	v_cndmask_b32_e64 v210, 0, v210, s[88:89]
	v_cndmask_b32_e64 v211, 0, v211, s[90:91]
	v_cndmask_b32_e64 v212, 0, v212, s[92:93]
	v_cndmask_b32_e64 v213, 0, v213, s[94:95]
	v_cndmask_b32_e64 v214, 0, v214, s[96:97]
	v_cndmask_b32_e64 v215, 0, v215, s[0:1]
	v_cndmask_b32_e64 v216, 0, v216, s[2:3]
	v_cndmask_b32_e64 v217, 0, v217, s[4:5]
	v_cndmask_b32_e64 v218, 0, v218, s[6:7]
	v_cndmask_b32_e64 v219, 0, v219, s[16:17]
.Lat1_t3_nomask:
	v_add_f32_e32 v189, v204, v205
	v_add_f32_e32 v190, v206, v207
	v_add_f32_e32 v191, v208, v209
	v_add_f32_e32 v192, v210, v211
	v_cvt_pk_bf16_f32 v204, v204, v205
	v_cvt_pk_bf16_f32 v205, v206, v207
	v_cvt_pk_bf16_f32 v206, v208, v209
	v_cvt_pk_bf16_f32 v207, v210, v211
	v_add_f32_e32 v193, v212, v213
	v_add_f32_e32 v194, v214, v215
	s_waitcnt lgkmcnt(4)
	v_mfma_f32_32x32x16_bf16 v[32:47], v[236:239], v[204:207], v[32:47]
	v_add_f32_e32 v195, v216, v217
	v_add_f32_e32 v196, v218, v219
	v_cvt_pk_bf16_f32 v208, v212, v213
	v_cvt_pk_bf16_f32 v209, v214, v215
	v_mfma_f32_32x32x16_bf16 v[16:31], v[244:247], v[204:207], v[16:31]
	v_cvt_pk_bf16_f32 v210, v216, v217
	v_cvt_pk_bf16_f32 v211, v218, v219
	v_add_f32_e32 v189, v189, v190
	v_add_f32_e32 v191, v191, v192
	v_mfma_f32_32x32x16_bf16 v[32:47], v[248:251], v[208:211], v[32:47]
	v_add_f32_e32 v193, v193, v194
	v_add_f32_e32 v195, v195, v196
	v_add_f32_e32 v189, v189, v191
	v_add_f32_e32 v193, v193, v195
	v_mfma_f32_32x32x16_bf16 v[16:31], v[252:255], v[208:211], v[16:31]
	v_add_f32_e32 v189, v189, v193
	v_add_f32_e32 v187, v187, v189
	ds_read2_b64 v[236:239], v199 offset1:2
	ds_read2_b64 v[244:247], v200 offset0:32 offset1:34
	ds_read2_b64 v[248:251], v199 offset0:4 offset1:6
	ds_read2_b64 v[252:255], v200 offset0:36 offset1:38
	v_add_u32_e32 v199, 64, v199
	v_add_u32_e32 v200, 64, v200
.Lat1_done:

	s_xor_b32 s33, s33, 1
	s_and_b64 vcc, exec, s[12:13]
	s_cbranch_vccz .LBB0_1200
	s_mul_i32 s0, s33, 0x8a00
	s_add_i32 s0, s0, 0
	v_add3_u32 v80, s0, v178, v144
	s_waitcnt vmcnt(2)
	ds_write_b128 v80, v[116:119]
	ds_write_b128 v80, v[112:115] offset:16
	v_lshl_add_u32 v80, v152, 1, s0
	s_waitcnt vmcnt(1)
	ds_write_b16 v80, v120 offset:18432
	ds_write_b16_d16_hi v80, v120 offset:18696
	ds_write_b16 v80, v121 offset:18960
	ds_write_b16_d16_hi v80, v121 offset:19224
	ds_write_b16 v80, v122 offset:19488
	ds_write_b16_d16_hi v80, v122 offset:19752
	ds_write_b16 v80, v123 offset:20016
	ds_write_b16_d16_hi v80, v123 offset:20280
	s_waitcnt vmcnt(0)
	ds_write_b16 v80, v124 offset:26880
	ds_write_b16_d16_hi v80, v124 offset:27144
	ds_write_b16 v80, v125 offset:27408
	ds_write_b16_d16_hi v80, v125 offset:27672
	ds_write_b16 v80, v126 offset:27936
	ds_write_b16_d16_hi v80, v126 offset:28200
	ds_write_b16 v80, v127 offset:28464
	ds_write_b16_d16_hi v80, v127 offset:28728

	.amdhsa_kernel _Z14fwd_megakernel1P
		.amdhsa_group_segment_fixed_size 0
		.amdhsa_private_segment_fixed_size 0
		.amdhsa_kernarg_size 520
		.amdhsa_user_sgpr_count 2
		.amdhsa_user_sgpr_dispatch_ptr 0
		.amdhsa_user_sgpr_queue_ptr 0
		.amdhsa_user_sgpr_kernarg_segment_ptr 1
		.amdhsa_user_sgpr_dispatch_id 0
		.amdhsa_user_sgpr_kernarg_preload_length 0
		.amdhsa_user_sgpr_kernarg_preload_offset 0
		.amdhsa_user_sgpr_private_segment_size 0
		.amdhsa_uses_dynamic_stack 0
		.amdhsa_enable_private_segment 0
		.amdhsa_system_sgpr_workgroup_id_x 1
		.amdhsa_system_sgpr_workgroup_id_y 0
		.amdhsa_system_sgpr_workgroup_id_z 0
		.amdhsa_system_sgpr_workgroup_info 0
		.amdhsa_system_vgpr_workitem_id 2
		.amdhsa_next_free_vgpr 256
		.amdhsa_next_free_sgpr 98
		.amdhsa_accum_offset 256
		.amdhsa_reserve_vcc 1
		.amdhsa_float_round_mode_32 0
		.amdhsa_float_round_mode_16_64 0
		.amdhsa_float_denorm_mode_32 3
		.amdhsa_float_denorm_mode_16_64 3
		.amdhsa_dx10_clamp 1
		.amdhsa_ieee_mode 1
		.amdhsa_fp16_overflow 0
		.amdhsa_tg_split 0
		.amdhsa_exception_fp_ieee_invalid_op 0
		.amdhsa_exception_fp_denorm_src 0
		.amdhsa_exception_fp_ieee_div_zero 0
		.amdhsa_exception_fp_ieee_overflow 0
		.amdhsa_exception_fp_ieee_underflow 0
		.amdhsa_exception_fp_ieee_inexact 0
		.amdhsa_exception_int_div_zero 0
	.end_amdhsa_kernel

amdhsa.kernels:
  - .agpr_count:     0
    .args:
      - .offset:         0
        .size:           264
        .value_kind:     by_value
      - .offset:         264
        .size:           4
        .value_kind:     hidden_block_count_x
      - .offset:         268
        .size:           4
        .value_kind:     hidden_block_count_y
      - .offset:         272
        .size:           4
        .value_kind:     hidden_block_count_z
      - .offset:         276
        .size:           2
        .value_kind:     hidden_group_size_x
      - .offset:         278
        .size:           2
        .value_kind:     hidden_group_size_y
      - .offset:         280
        .size:           2
        .value_kind:     hidden_group_size_z
      - .offset:         282
        .size:           2
        .value_kind:     hidden_remainder_x
      - .offset:         284
        .size:           2
        .value_kind:     hidden_remainder_y
      - .offset:         286
        .size:           2
        .value_kind:     hidden_remainder_z
      - .offset:         304
        .size:           8
        .value_kind:     hidden_global_offset_x
      - .offset:         312
        .size:           8
        .value_kind:     hidden_global_offset_y
      - .offset:         320
        .size:           8
        .value_kind:     hidden_global_offset_z
      - .offset:         328
        .size:           2
        .value_kind:     hidden_grid_dims
      - .offset:         352
        .size:           8
        .value_kind:     hidden_multigrid_sync_arg
      - .offset:         384
        .size:           4
        .value_kind:     hidden_dynamic_lds_size
    .group_segment_fixed_size: 0
    .kernarg_segment_align: 8
    .kernarg_segment_size: 520
    .language:       OpenCL C
    .language_version:
      - 2
      - 0
    .max_flat_workgroup_size: 512
    .name:           _Z14fwd_megakernel1P
    .private_segment_fixed_size: 0
    .sgpr_count:     104
    .sgpr_spill_count: 117
    .symbol:         _Z14fwd_megakernel1P.kd
    .uniform_work_group_size: 1
    .uses_dynamic_stack: false
    .vgpr_count:     256
    .vgpr_spill_count: 0
    .wavefront_size: 64
